# PH8 epilogue rewritten by hand: packed f32 mul/add for the sigmoid argument and +1, SGPR-base stores, staged schedule (same per-element math)
# speedup vs baseline: 1.0025x; 1.0025x over previous
; #define SBAR() __builtin_amdgcn_sched_barrier(0)
; __device__ __forceinline__ float fast_sigmoid(float x) { return __builtin_amdgcn_rcpf(1.0f + __builtin_amdgcn_exp2f(-1.4426950408889634f * x)); }
; __device__ __forceinline__ u32x4 pack8(const f32x4 a, const f32x4 b) { u32x4 w; w.x = cvt_pk_bf16(a[0], a[1]); w.y = cvt_pk_bf16(a[2], a[3]); w.z = cvt_pk_bf16(b[0], b[1]); w.w = cvt_pk_bf16(b[2], b[3]); return w; }
;     __device__ __forceinline__ void operator()(f32x4 (&acc)[2][2][4][2], const Unit& u, int wr, int wc, int fr, int fq) const {
;     ...
;             float rsv[8];
; #pragma unroll
;             for (int i = 0; i < 8; ++i) rsv[i] = P.ssq_h1_()[ROWOF(i >> 2, i & 3)];
;             SBAR();
; #pragma unroll
;             for (int ai = 0; ai < 2; ++ai)
; #pragma unroll
;                 for (int m = 0; m < 4; ++m) { const int row = ROWOF(ai, m); const float rs = rsqrtf(rsv[ai * 4 + m] * (1.0f / 2048.0f) + EPS);
;                     f32x4 g0 = acc[ai][0][m][0] * rs, g1 = acc[ai][0][m][1] * rs; const f32x4 u0 = acc[ai][1][m][0] * rs, u1 = acc[ai][1][m][1] * rs;
; #pragma unroll
;                     for (int j = 0; j < 4; ++j) { g0[j] = g0[j] * fast_sigmoid(g0[j]) * u0[j]; g1[j] = g1[j] * fast_sigmoid(g1[j]) * u1[j]; }
;                     *(u32x4*)(P.f_() + (size_t)row * DFF + u.pn * 128 + c8) = pack8(g0, g1); }
.LBB0_1002:
	v_lshl_add_u32 v146, s22, 8, v150
	v_ashrrev_i32_e32 v147, 31, v146
	v_lshl_add_u64 v[156:157], v[146:147], 2, s[10:11]
	global_load_dword v158, v[156:157], off
	global_load_dword v159, v[156:157], off offset:64
	global_load_dword v164, v[156:157], off offset:128
	global_load_dword v165, v[156:157], off offset:192
	global_load_dword v166, v[156:157], off offset:512
	global_load_dword v149, v[156:157], off offset:576
	global_load_dword v148, v[156:157], off offset:640
	global_load_dword v147, v[156:157], off offset:704
	v_add_u32_e32 v156, 0x80, v146
	s_waitcnt vmcnt(0)
	s_lshl_b32 s22, s23, 7
	s_ashr_i32 s23, s22, 31
	s_lshl_b64 s[22:23], s[22:23], 1
	s_add_u32 s98, s12, s22
	s_addc_u32 s99, s13, s23
	s_mov_b32 s36, 0xbfb8aa3b
	s_mov_b32 s37, 0xbfb8aa3b
	s_mov_b32 s38, 1.0
	s_mov_b32 s39, 1.0
	v_fmamk_f32 v228, v158, 0x3a000000, v155
	v_mul_f32_e32 v229, 0x4b800000, v228
	v_cmp_gt_f32_e32 vcc, s51, v228
	s_nop 1
	v_cndmask_b32_e32 v228, v228, v229, vcc
	v_mad_u32_u24 v157, v146, s52, v134
	v_rsq_f32_e32 v228, v228
	s_nop 0
	v_mul_f32_e32 v229, 0x45800000, v228
	s_nop 0
	v_cndmask_b32_e32 v228, v228, v229, vcc
	v_pk_mul_f32 v[126:127], v[126:127], v[228:229] op_sel_hi:[1,0]
	v_pk_mul_f32 v[128:129], v[128:129], v[228:229] op_sel_hi:[1,0]
	v_pk_mul_f32 v[122:123], v[122:123], v[228:229] op_sel_hi:[1,0]
	v_pk_mul_f32 v[124:125], v[124:125], v[228:229] op_sel_hi:[1,0]
	v_pk_mul_f32 v[118:119], v[118:119], v[228:229] op_sel_hi:[1,0]
	v_pk_mul_f32 v[120:121], v[120:121], v[228:229] op_sel_hi:[1,0]
	v_pk_mul_f32 v[114:115], v[114:115], v[228:229] op_sel_hi:[1,0]
	v_pk_mul_f32 v[116:117], v[116:117], v[228:229] op_sel_hi:[1,0]
	v_pk_mul_f32 v[220:221], v[126:127], s[36:37]
	v_pk_mul_f32 v[222:223], v[128:129], s[36:37]
	v_pk_mul_f32 v[224:225], v[122:123], s[36:37]
	v_pk_mul_f32 v[226:227], v[124:125], s[36:37]
	v_exp_f32_e32 v220, v220
	v_exp_f32_e32 v221, v221
	v_exp_f32_e32 v222, v222
	v_exp_f32_e32 v223, v223
	v_exp_f32_e32 v224, v224
	v_exp_f32_e32 v225, v225
	v_exp_f32_e32 v226, v226
	v_exp_f32_e32 v227, v227
	v_pk_add_f32 v[220:221], v[220:221], s[38:39]
	v_pk_add_f32 v[222:223], v[222:223], s[38:39]
	v_pk_add_f32 v[224:225], v[224:225], s[38:39]
	v_pk_add_f32 v[226:227], v[226:227], s[38:39]
	v_rcp_f32_e32 v220, v220
	v_rcp_f32_e32 v221, v221
	v_rcp_f32_e32 v222, v222
	v_rcp_f32_e32 v223, v223
	v_rcp_f32_e32 v224, v224
	v_rcp_f32_e32 v225, v225
	v_rcp_f32_e32 v226, v226
	v_rcp_f32_e32 v227, v227
	v_pk_mul_f32 v[126:127], v[126:127], v[220:221]
	v_pk_mul_f32 v[128:129], v[128:129], v[222:223]
	v_pk_mul_f32 v[122:123], v[122:123], v[224:225]
	v_pk_mul_f32 v[124:125], v[124:125], v[226:227]
	v_pk_mul_f32 v[118:119], v[118:119], v[126:127]
	v_pk_mul_f32 v[120:121], v[120:121], v[128:129]
	v_pk_mul_f32 v[114:115], v[114:115], v[122:123]
	v_pk_mul_f32 v[116:117], v[116:117], v[124:125]
	v_cvt_pk_bf16_f32 v126, v118, v119
	v_cvt_pk_bf16_f32 v127, v120, v121
	v_cvt_pk_bf16_f32 v128, v114, v115
	v_cvt_pk_bf16_f32 v129, v116, v117
	global_store_dwordx4 v157, v[126:129], s[98:99]
	v_fmamk_f32 v228, v159, 0x3a000000, v155
	v_mul_f32_e32 v229, 0x4b800000, v228
	v_cmp_gt_f32_e32 vcc, s51, v228
	v_or_b32_e32 v156, 0x10, v146
	s_nop 0
	v_cndmask_b32_e32 v228, v228, v229, vcc
	v_mad_u32_u24 v160, v156, s52, v134
	v_rsq_f32_e32 v228, v228
	s_nop 0
	v_mul_f32_e32 v229, 0x45800000, v228
	s_nop 0
	v_cndmask_b32_e32 v228, v228, v229, vcc
	v_pk_mul_f32 v[110:111], v[110:111], v[228:229] op_sel_hi:[1,0]
	v_pk_mul_f32 v[112:113], v[112:113], v[228:229] op_sel_hi:[1,0]
	v_pk_mul_f32 v[106:107], v[106:107], v[228:229] op_sel_hi:[1,0]
	v_pk_mul_f32 v[108:109], v[108:109], v[228:229] op_sel_hi:[1,0]
	v_pk_mul_f32 v[102:103], v[102:103], v[228:229] op_sel_hi:[1,0]
	v_pk_mul_f32 v[104:105], v[104:105], v[228:229] op_sel_hi:[1,0]
	v_pk_mul_f32 v[98:99], v[98:99], v[228:229] op_sel_hi:[1,0]
	v_pk_mul_f32 v[100:101], v[100:101], v[228:229] op_sel_hi:[1,0]
	v_pk_mul_f32 v[220:221], v[110:111], s[36:37]
	v_pk_mul_f32 v[222:223], v[112:113], s[36:37]
	v_pk_mul_f32 v[224:225], v[106:107], s[36:37]
	v_pk_mul_f32 v[226:227], v[108:109], s[36:37]
	v_exp_f32_e32 v220, v220
	v_exp_f32_e32 v221, v221
	v_exp_f32_e32 v222, v222
	v_exp_f32_e32 v223, v223
	v_exp_f32_e32 v224, v224
	v_exp_f32_e32 v225, v225
	v_exp_f32_e32 v226, v226
	v_exp_f32_e32 v227, v227
	v_pk_add_f32 v[220:221], v[220:221], s[38:39]
	v_pk_add_f32 v[222:223], v[222:223], s[38:39]
	v_pk_add_f32 v[224:225], v[224:225], s[38:39]
	v_pk_add_f32 v[226:227], v[226:227], s[38:39]
	v_rcp_f32_e32 v220, v220
	v_rcp_f32_e32 v221, v221
	v_rcp_f32_e32 v222, v222
	v_rcp_f32_e32 v223, v223
	v_rcp_f32_e32 v224, v224
	v_rcp_f32_e32 v225, v225
	v_rcp_f32_e32 v226, v226
	v_rcp_f32_e32 v227, v227
	v_pk_mul_f32 v[110:111], v[110:111], v[220:221]
	v_pk_mul_f32 v[112:113], v[112:113], v[222:223]
	v_pk_mul_f32 v[106:107], v[106:107], v[224:225]
	v_pk_mul_f32 v[108:109], v[108:109], v[226:227]
	v_pk_mul_f32 v[102:103], v[102:103], v[110:111]
	v_pk_mul_f32 v[104:105], v[104:105], v[112:113]
	v_pk_mul_f32 v[98:99], v[98:99], v[106:107]
	v_pk_mul_f32 v[100:101], v[100:101], v[108:109]
	v_cvt_pk_bf16_f32 v110, v102, v103
	v_cvt_pk_bf16_f32 v111, v104, v105
	v_cvt_pk_bf16_f32 v112, v98, v99
	v_cvt_pk_bf16_f32 v113, v100, v101
	global_store_dwordx4 v160, v[110:113], s[98:99]
	v_fmamk_f32 v228, v164, 0x3a000000, v155
	v_mul_f32_e32 v229, 0x4b800000, v228
	v_cmp_gt_f32_e32 vcc, s51, v228
	v_or_b32_e32 v156, 0x20, v146
	s_nop 0
	v_cndmask_b32_e32 v228, v228, v229, vcc
	v_mad_u32_u24 v157, v156, s52, v134
	v_rsq_f32_e32 v228, v228
	s_nop 0
	v_mul_f32_e32 v229, 0x45800000, v228
	s_nop 0
	v_cndmask_b32_e32 v228, v228, v229, vcc
; __device__ __forceinline__ float fast_sigmoid(float x) { return __builtin_amdgcn_rcpf(1.0f + __builtin_amdgcn_exp2f(-1.4426950408889634f * x)); }
; __device__ __forceinline__ u32x4 pack8(const f32x4 a, const f32x4 b) { u32x4 w; w.x = cvt_pk_bf16(a[0], a[1]); w.y = cvt_pk_bf16(a[2], a[3]); w.z = cvt_pk_bf16(b[0], b[1]); w.w = cvt_pk_bf16(b[2], b[3]); return w; }
;     __device__ __forceinline__ void operator()(f32x4 (&acc)[2][2][4][2], const Unit& u, int wr, int wc, int fr, int fq) const {
;     ...
;                 for (int m = 0; m < 4; ++m) { const int row = ROWOF(ai, m); const float rs = rsqrtf(rsv[ai * 4 + m] * (1.0f / 2048.0f) + EPS);
;                     f32x4 g0 = acc[ai][0][m][0] * rs, g1 = acc[ai][0][m][1] * rs; const f32x4 u0 = acc[ai][1][m][0] * rs, u1 = acc[ai][1][m][1] * rs;
; #pragma unroll
;                     for (int j = 0; j < 4; ++j) { g0[j] = g0[j] * fast_sigmoid(g0[j]) * u0[j]; g1[j] = g1[j] * fast_sigmoid(g1[j]) * u1[j]; }
;                     *(u32x4*)(P.f_() + (size_t)row * DFF + u.pn * 128 + c8) = pack8(g0, g1); }
	v_pk_mul_f32 v[94:95], v[94:95], v[228:229] op_sel_hi:[1,0]
	v_pk_mul_f32 v[96:97], v[96:97], v[228:229] op_sel_hi:[1,0]
	v_pk_mul_f32 v[90:91], v[90:91], v[228:229] op_sel_hi:[1,0]
	v_pk_mul_f32 v[92:93], v[92:93], v[228:229] op_sel_hi:[1,0]
	v_pk_mul_f32 v[86:87], v[86:87], v[228:229] op_sel_hi:[1,0]
	v_pk_mul_f32 v[88:89], v[88:89], v[228:229] op_sel_hi:[1,0]
	v_pk_mul_f32 v[82:83], v[82:83], v[228:229] op_sel_hi:[1,0]
	v_pk_mul_f32 v[84:85], v[84:85], v[228:229] op_sel_hi:[1,0]
	v_pk_mul_f32 v[220:221], v[94:95], s[36:37]
	v_pk_mul_f32 v[222:223], v[96:97], s[36:37]
	v_pk_mul_f32 v[224:225], v[90:91], s[36:37]
	v_pk_mul_f32 v[226:227], v[92:93], s[36:37]
	v_exp_f32_e32 v220, v220
	v_exp_f32_e32 v221, v221
	v_exp_f32_e32 v222, v222
	v_exp_f32_e32 v223, v223
	v_exp_f32_e32 v224, v224
	v_exp_f32_e32 v225, v225
	v_exp_f32_e32 v226, v226
	v_exp_f32_e32 v227, v227
	v_pk_add_f32 v[220:221], v[220:221], s[38:39]
	v_pk_add_f32 v[222:223], v[222:223], s[38:39]
	v_pk_add_f32 v[224:225], v[224:225], s[38:39]
	v_pk_add_f32 v[226:227], v[226:227], s[38:39]
	v_rcp_f32_e32 v220, v220
	v_rcp_f32_e32 v221, v221
	v_rcp_f32_e32 v222, v222
	v_rcp_f32_e32 v223, v223
	v_rcp_f32_e32 v224, v224
	v_rcp_f32_e32 v225, v225
	v_rcp_f32_e32 v226, v226
	v_rcp_f32_e32 v227, v227
	v_pk_mul_f32 v[94:95], v[94:95], v[220:221]
	v_pk_mul_f32 v[96:97], v[96:97], v[222:223]
	v_pk_mul_f32 v[90:91], v[90:91], v[224:225]
	v_pk_mul_f32 v[92:93], v[92:93], v[226:227]
	v_pk_mul_f32 v[86:87], v[86:87], v[94:95]
	v_pk_mul_f32 v[88:89], v[88:89], v[96:97]
	v_pk_mul_f32 v[82:83], v[82:83], v[90:91]
	v_pk_mul_f32 v[84:85], v[84:85], v[92:93]
	v_cvt_pk_bf16_f32 v94, v86, v87
	v_cvt_pk_bf16_f32 v95, v88, v89
	v_cvt_pk_bf16_f32 v96, v82, v83
	v_cvt_pk_bf16_f32 v97, v84, v85
	global_store_dwordx4 v157, v[94:97], s[98:99]
	v_fmamk_f32 v228, v165, 0x3a000000, v155
	v_mul_f32_e32 v229, 0x4b800000, v228
	v_cmp_gt_f32_e32 vcc, s51, v228
	v_or_b32_e32 v156, 0x30, v146
	s_nop 0
	v_cndmask_b32_e32 v228, v228, v229, vcc
	v_mad_u32_u24 v160, v156, s52, v134
	v_rsq_f32_e32 v228, v228
	s_nop 0
	v_mul_f32_e32 v229, 0x45800000, v228
	s_nop 0
	v_cndmask_b32_e32 v228, v228, v229, vcc
	v_pk_mul_f32 v[78:79], v[78:79], v[228:229] op_sel_hi:[1,0]
	v_pk_mul_f32 v[80:81], v[80:81], v[228:229] op_sel_hi:[1,0]
	v_pk_mul_f32 v[74:75], v[74:75], v[228:229] op_sel_hi:[1,0]
	v_pk_mul_f32 v[76:77], v[76:77], v[228:229] op_sel_hi:[1,0]
	v_pk_mul_f32 v[70:71], v[70:71], v[228:229] op_sel_hi:[1,0]
	v_pk_mul_f32 v[72:73], v[72:73], v[228:229] op_sel_hi:[1,0]
	v_pk_mul_f32 v[66:67], v[66:67], v[228:229] op_sel_hi:[1,0]
	v_pk_mul_f32 v[68:69], v[68:69], v[228:229] op_sel_hi:[1,0]
	v_pk_mul_f32 v[220:221], v[78:79], s[36:37]
	v_pk_mul_f32 v[222:223], v[80:81], s[36:37]
	v_pk_mul_f32 v[224:225], v[74:75], s[36:37]
	v_pk_mul_f32 v[226:227], v[76:77], s[36:37]
	v_exp_f32_e32 v220, v220
	v_exp_f32_e32 v221, v221
	v_exp_f32_e32 v222, v222
	v_exp_f32_e32 v223, v223
	v_exp_f32_e32 v224, v224
	v_exp_f32_e32 v225, v225
	v_exp_f32_e32 v226, v226
	v_exp_f32_e32 v227, v227
	v_pk_add_f32 v[220:221], v[220:221], s[38:39]
	v_pk_add_f32 v[222:223], v[222:223], s[38:39]
	v_pk_add_f32 v[224:225], v[224:225], s[38:39]
	v_pk_add_f32 v[226:227], v[226:227], s[38:39]
	v_rcp_f32_e32 v220, v220
	v_rcp_f32_e32 v221, v221
	v_rcp_f32_e32 v222, v222
	v_rcp_f32_e32 v223, v223
	v_rcp_f32_e32 v224, v224
	v_rcp_f32_e32 v225, v225
	v_rcp_f32_e32 v226, v226
	v_rcp_f32_e32 v227, v227
	v_pk_mul_f32 v[78:79], v[78:79], v[220:221]
	v_pk_mul_f32 v[80:81], v[80:81], v[222:223]
	v_pk_mul_f32 v[74:75], v[74:75], v[224:225]
	v_pk_mul_f32 v[76:77], v[76:77], v[226:227]
	v_pk_mul_f32 v[70:71], v[70:71], v[78:79]
	v_pk_mul_f32 v[72:73], v[72:73], v[80:81]
	v_pk_mul_f32 v[66:67], v[66:67], v[74:75]
	v_pk_mul_f32 v[68:69], v[68:69], v[76:77]
	v_cvt_pk_bf16_f32 v78, v70, v71
	v_cvt_pk_bf16_f32 v79, v72, v73
	v_cvt_pk_bf16_f32 v80, v66, v67
	v_cvt_pk_bf16_f32 v81, v68, v69
	global_store_dwordx4 v160, v[78:81], s[98:99]
	v_fmamk_f32 v228, v166, 0x3a000000, v155
	v_mul_f32_e32 v229, 0x4b800000, v228
	v_cmp_gt_f32_e32 vcc, s51, v228
	v_add_u32_e32 v156, 0x80, v146
	s_nop 0
	v_cndmask_b32_e32 v228, v228, v229, vcc
	v_mad_u32_u24 v157, v156, s52, v134
	v_rsq_f32_e32 v228, v228
	s_nop 0
	v_mul_f32_e32 v229, 0x45800000, v228
	s_nop 0
	v_cndmask_b32_e32 v228, v228, v229, vcc
	v_pk_mul_f32 v[62:63], v[62:63], v[228:229] op_sel_hi:[1,0]
	v_pk_mul_f32 v[64:65], v[64:65], v[228:229] op_sel_hi:[1,0]
	v_pk_mul_f32 v[58:59], v[58:59], v[228:229] op_sel_hi:[1,0]
	v_pk_mul_f32 v[60:61], v[60:61], v[228:229] op_sel_hi:[1,0]
	v_pk_mul_f32 v[54:55], v[54:55], v[228:229] op_sel_hi:[1,0]
	v_pk_mul_f32 v[56:57], v[56:57], v[228:229] op_sel_hi:[1,0]
	v_pk_mul_f32 v[50:51], v[50:51], v[228:229] op_sel_hi:[1,0]
	v_pk_mul_f32 v[52:53], v[52:53], v[228:229] op_sel_hi:[1,0]
	v_pk_mul_f32 v[220:221], v[62:63], s[36:37]
	v_pk_mul_f32 v[222:223], v[64:65], s[36:37]
	v_pk_mul_f32 v[224:225], v[58:59], s[36:37]
	v_pk_mul_f32 v[226:227], v[60:61], s[36:37]
	v_exp_f32_e32 v220, v220
	v_exp_f32_e32 v221, v221
	v_exp_f32_e32 v222, v222
	v_exp_f32_e32 v223, v223
	v_exp_f32_e32 v224, v224
	v_exp_f32_e32 v225, v225
	v_exp_f32_e32 v226, v226
	v_exp_f32_e32 v227, v227
	v_pk_add_f32 v[220:221], v[220:221], s[38:39]
	v_pk_add_f32 v[222:223], v[222:223], s[38:39]
	v_pk_add_f32 v[224:225], v[224:225], s[38:39]
	v_pk_add_f32 v[226:227], v[226:227], s[38:39]
	v_rcp_f32_e32 v220, v220
	v_rcp_f32_e32 v221, v221
	v_rcp_f32_e32 v222, v222
	v_rcp_f32_e32 v223, v223
	v_rcp_f32_e32 v224, v224
	v_rcp_f32_e32 v225, v225
	v_rcp_f32_e32 v226, v226
	v_rcp_f32_e32 v227, v227
	v_pk_mul_f32 v[62:63], v[62:63], v[220:221]
; __device__ __forceinline__ float fast_sigmoid(float x) { return __builtin_amdgcn_rcpf(1.0f + __builtin_amdgcn_exp2f(-1.4426950408889634f * x)); }
; __device__ __forceinline__ u32x4 pack8(const f32x4 a, const f32x4 b) { u32x4 w; w.x = cvt_pk_bf16(a[0], a[1]); w.y = cvt_pk_bf16(a[2], a[3]); w.z = cvt_pk_bf16(b[0], b[1]); w.w = cvt_pk_bf16(b[2], b[3]); return w; }
; template <class Sched, class Epi>
; __device__ __forceinline__ void gemm_run(LAS unsigned char* lds, const Sched& S, const Epi& E) {
;     ...
;         if constexpr (!Epi::AFTER_DRAIN) E(acc, cur, wr, wc, fr, fq);
;         if (!has_next) break;
;     __device__ __forceinline__ void operator()(f32x4 (&acc)[2][2][4][2], const Unit& u, int wr, int wc, int fr, int fq) const {
;     ...
;                 for (int m = 0; m < 4; ++m) { const int row = ROWOF(ai, m); const float rs = rsqrtf(rsv[ai * 4 + m] * (1.0f / 2048.0f) + EPS);
;                     f32x4 g0 = acc[ai][0][m][0] * rs, g1 = acc[ai][0][m][1] * rs; const f32x4 u0 = acc[ai][1][m][0] * rs, u1 = acc[ai][1][m][1] * rs;
; #pragma unroll
;                     for (int j = 0; j < 4; ++j) { g0[j] = g0[j] * fast_sigmoid(g0[j]) * u0[j]; g1[j] = g1[j] * fast_sigmoid(g1[j]) * u1[j]; }
;                     *(u32x4*)(P.f_() + (size_t)row * DFF + u.pn * 128 + c8) = pack8(g0, g1); }
	v_pk_mul_f32 v[64:65], v[64:65], v[222:223]
	v_pk_mul_f32 v[58:59], v[58:59], v[224:225]
	v_pk_mul_f32 v[60:61], v[60:61], v[226:227]
	v_pk_mul_f32 v[54:55], v[54:55], v[62:63]
	v_pk_mul_f32 v[56:57], v[56:57], v[64:65]
	v_pk_mul_f32 v[50:51], v[50:51], v[58:59]
	v_pk_mul_f32 v[52:53], v[52:53], v[60:61]
	v_cvt_pk_bf16_f32 v62, v54, v55
	v_cvt_pk_bf16_f32 v63, v56, v57
	v_cvt_pk_bf16_f32 v64, v50, v51
	v_cvt_pk_bf16_f32 v65, v52, v53
	global_store_dwordx4 v157, v[62:65], s[98:99]
	v_fmamk_f32 v228, v149, 0x3a000000, v155
	v_mul_f32_e32 v229, 0x4b800000, v228
	v_cmp_gt_f32_e32 vcc, s51, v228
	v_add_u32_e32 v156, 0x90, v146
	s_nop 0
	v_cndmask_b32_e32 v228, v228, v229, vcc
	v_mad_u32_u24 v160, v156, s52, v134
	v_rsq_f32_e32 v228, v228
	s_nop 0
	v_mul_f32_e32 v229, 0x45800000, v228
	s_nop 0
	v_cndmask_b32_e32 v228, v228, v229, vcc
	v_pk_mul_f32 v[46:47], v[46:47], v[228:229] op_sel_hi:[1,0]
	v_pk_mul_f32 v[48:49], v[48:49], v[228:229] op_sel_hi:[1,0]
	v_pk_mul_f32 v[42:43], v[42:43], v[228:229] op_sel_hi:[1,0]
	v_pk_mul_f32 v[44:45], v[44:45], v[228:229] op_sel_hi:[1,0]
	v_pk_mul_f32 v[38:39], v[38:39], v[228:229] op_sel_hi:[1,0]
	v_pk_mul_f32 v[40:41], v[40:41], v[228:229] op_sel_hi:[1,0]
	v_pk_mul_f32 v[34:35], v[34:35], v[228:229] op_sel_hi:[1,0]
	v_pk_mul_f32 v[36:37], v[36:37], v[228:229] op_sel_hi:[1,0]
	v_pk_mul_f32 v[220:221], v[46:47], s[36:37]
	v_pk_mul_f32 v[222:223], v[48:49], s[36:37]
	v_pk_mul_f32 v[224:225], v[42:43], s[36:37]
	v_pk_mul_f32 v[226:227], v[44:45], s[36:37]
	v_exp_f32_e32 v220, v220
	v_exp_f32_e32 v221, v221
	v_exp_f32_e32 v222, v222
	v_exp_f32_e32 v223, v223
	v_exp_f32_e32 v224, v224
	v_exp_f32_e32 v225, v225
	v_exp_f32_e32 v226, v226
	v_exp_f32_e32 v227, v227
	v_pk_add_f32 v[220:221], v[220:221], s[38:39]
	v_pk_add_f32 v[222:223], v[222:223], s[38:39]
	v_pk_add_f32 v[224:225], v[224:225], s[38:39]
	v_pk_add_f32 v[226:227], v[226:227], s[38:39]
	v_rcp_f32_e32 v220, v220
	v_rcp_f32_e32 v221, v221
	v_rcp_f32_e32 v222, v222
	v_rcp_f32_e32 v223, v223
	v_rcp_f32_e32 v224, v224
	v_rcp_f32_e32 v225, v225
	v_rcp_f32_e32 v226, v226
	v_rcp_f32_e32 v227, v227
	v_pk_mul_f32 v[46:47], v[46:47], v[220:221]
	v_pk_mul_f32 v[48:49], v[48:49], v[222:223]
	v_pk_mul_f32 v[42:43], v[42:43], v[224:225]
	v_pk_mul_f32 v[44:45], v[44:45], v[226:227]
	v_pk_mul_f32 v[38:39], v[38:39], v[46:47]
	v_pk_mul_f32 v[40:41], v[40:41], v[48:49]
	v_pk_mul_f32 v[34:35], v[34:35], v[42:43]
	v_pk_mul_f32 v[36:37], v[36:37], v[44:45]
	v_cvt_pk_bf16_f32 v46, v38, v39
	v_cvt_pk_bf16_f32 v47, v40, v41
	v_cvt_pk_bf16_f32 v48, v34, v35
	v_cvt_pk_bf16_f32 v49, v36, v37
	global_store_dwordx4 v160, v[46:49], s[98:99]
	v_fmamk_f32 v228, v148, 0x3a000000, v155
	v_mul_f32_e32 v229, 0x4b800000, v228
	v_cmp_gt_f32_e32 vcc, s51, v228
	v_add_u32_e32 v156, 0xa0, v146
	s_nop 0
	v_cndmask_b32_e32 v228, v228, v229, vcc
	v_mad_u32_u24 v157, v156, s52, v134
	v_rsq_f32_e32 v228, v228
	s_nop 0
	v_mul_f32_e32 v229, 0x45800000, v228
	s_nop 0
	v_cndmask_b32_e32 v228, v228, v229, vcc
	v_pk_mul_f32 v[30:31], v[30:31], v[228:229] op_sel_hi:[1,0]
	v_pk_mul_f32 v[32:33], v[32:33], v[228:229] op_sel_hi:[1,0]
	v_pk_mul_f32 v[26:27], v[26:27], v[228:229] op_sel_hi:[1,0]
	v_pk_mul_f32 v[28:29], v[28:29], v[228:229] op_sel_hi:[1,0]
	v_pk_mul_f32 v[22:23], v[22:23], v[228:229] op_sel_hi:[1,0]
	v_pk_mul_f32 v[24:25], v[24:25], v[228:229] op_sel_hi:[1,0]
	v_pk_mul_f32 v[18:19], v[18:19], v[228:229] op_sel_hi:[1,0]
	v_pk_mul_f32 v[20:21], v[20:21], v[228:229] op_sel_hi:[1,0]
	v_pk_mul_f32 v[220:221], v[30:31], s[36:37]
	v_pk_mul_f32 v[222:223], v[32:33], s[36:37]
	v_pk_mul_f32 v[224:225], v[26:27], s[36:37]
	v_pk_mul_f32 v[226:227], v[28:29], s[36:37]
	v_exp_f32_e32 v220, v220
	v_exp_f32_e32 v221, v221
	v_exp_f32_e32 v222, v222
	v_exp_f32_e32 v223, v223
	v_exp_f32_e32 v224, v224
	v_exp_f32_e32 v225, v225
	v_exp_f32_e32 v226, v226
	v_exp_f32_e32 v227, v227
	v_pk_add_f32 v[220:221], v[220:221], s[38:39]
	v_pk_add_f32 v[222:223], v[222:223], s[38:39]
	v_pk_add_f32 v[224:225], v[224:225], s[38:39]
	v_pk_add_f32 v[226:227], v[226:227], s[38:39]
	v_rcp_f32_e32 v220, v220
	v_rcp_f32_e32 v221, v221
	v_rcp_f32_e32 v222, v222
	v_rcp_f32_e32 v223, v223
	v_rcp_f32_e32 v224, v224
	v_rcp_f32_e32 v225, v225
	v_rcp_f32_e32 v226, v226
	v_rcp_f32_e32 v227, v227
	v_pk_mul_f32 v[30:31], v[30:31], v[220:221]
	v_pk_mul_f32 v[32:33], v[32:33], v[222:223]
	v_pk_mul_f32 v[26:27], v[26:27], v[224:225]
	v_pk_mul_f32 v[28:29], v[28:29], v[226:227]
	v_pk_mul_f32 v[22:23], v[22:23], v[30:31]
	v_pk_mul_f32 v[24:25], v[24:25], v[32:33]
	v_pk_mul_f32 v[18:19], v[18:19], v[26:27]
	v_pk_mul_f32 v[20:21], v[20:21], v[28:29]
	v_cvt_pk_bf16_f32 v30, v22, v23
	v_cvt_pk_bf16_f32 v31, v24, v25
	v_cvt_pk_bf16_f32 v32, v18, v19
	v_cvt_pk_bf16_f32 v33, v20, v21
	global_store_dwordx4 v157, v[30:33], s[98:99]
	v_fmamk_f32 v228, v147, 0x3a000000, v155
	v_mul_f32_e32 v229, 0x4b800000, v228
	v_cmp_gt_f32_e32 vcc, s51, v228
	v_add_u32_e32 v156, 0xb0, v146
	s_nop 0
	v_cndmask_b32_e32 v228, v228, v229, vcc
	v_mad_u32_u24 v160, v156, s52, v134
	v_rsq_f32_e32 v228, v228
	s_nop 0
	v_mul_f32_e32 v229, 0x45800000, v228
	s_nop 0
	v_cndmask_b32_e32 v228, v228, v229, vcc
	v_pk_mul_f32 v[14:15], v[14:15], v[228:229] op_sel_hi:[1,0]
	v_pk_mul_f32 v[16:17], v[16:17], v[228:229] op_sel_hi:[1,0]
	v_pk_mul_f32 v[10:11], v[10:11], v[228:229] op_sel_hi:[1,0]
	v_pk_mul_f32 v[12:13], v[12:13], v[228:229] op_sel_hi:[1,0]
	v_pk_mul_f32 v[6:7], v[6:7], v[228:229] op_sel_hi:[1,0]
	v_pk_mul_f32 v[8:9], v[8:9], v[228:229] op_sel_hi:[1,0]
	v_pk_mul_f32 v[2:3], v[2:3], v[228:229] op_sel_hi:[1,0]
	v_pk_mul_f32 v[4:5], v[4:5], v[228:229] op_sel_hi:[1,0]
	v_pk_mul_f32 v[220:221], v[14:15], s[36:37]
	v_pk_mul_f32 v[222:223], v[16:17], s[36:37]
	v_pk_mul_f32 v[224:225], v[10:11], s[36:37]
	v_pk_mul_f32 v[226:227], v[12:13], s[36:37]
	v_exp_f32_e32 v220, v220
	v_exp_f32_e32 v221, v221
	v_exp_f32_e32 v222, v222
	v_exp_f32_e32 v223, v223
	v_exp_f32_e32 v224, v224
	v_exp_f32_e32 v225, v225
	v_exp_f32_e32 v226, v226
	v_exp_f32_e32 v227, v227
	v_pk_add_f32 v[220:221], v[220:221], s[38:39]
	v_pk_add_f32 v[222:223], v[222:223], s[38:39]
	v_pk_add_f32 v[224:225], v[224:225], s[38:39]
	v_pk_add_f32 v[226:227], v[226:227], s[38:39]
	v_rcp_f32_e32 v220, v220
	v_rcp_f32_e32 v221, v221
	v_rcp_f32_e32 v222, v222
	v_rcp_f32_e32 v223, v223
	v_rcp_f32_e32 v224, v224
	v_rcp_f32_e32 v225, v225
	v_rcp_f32_e32 v226, v226
	v_rcp_f32_e32 v227, v227
	v_pk_mul_f32 v[14:15], v[14:15], v[220:221]
	v_pk_mul_f32 v[16:17], v[16:17], v[222:223]
	v_pk_mul_f32 v[10:11], v[10:11], v[224:225]
	v_pk_mul_f32 v[12:13], v[12:13], v[226:227]
	v_pk_mul_f32 v[6:7], v[6:7], v[14:15]
	v_pk_mul_f32 v[8:9], v[8:9], v[16:17]
	v_pk_mul_f32 v[2:3], v[2:3], v[10:11]
	v_pk_mul_f32 v[4:5], v[4:5], v[12:13]
	v_cvt_pk_bf16_f32 v14, v6, v7
	v_cvt_pk_bf16_f32 v15, v8, v9
	v_cvt_pk_bf16_f32 v16, v2, v3
	v_cvt_pk_bf16_f32 v17, v4, v5
	s_andn2_b64 vcc, exec, s[18:19]
	s_mov_b64 s[18:19], -1
	global_store_dwordx4 v160, v[14:17], s[98:99]
	s_cbranch_vccnz .LBB0_995
; #define PG8_BAR __builtin_amdgcn_s_barrier()
; template <class Sched, class Epi>
; __device__ __forceinline__ void gemm_run(LAS unsigned char* lds, const Sched& S, const Epi& E) {
;     ...
;         if constexpr (!Epi::AFTER_DRAIN) E(acc, cur, wr, wc, fr, fq);
;         if (!has_next) break;
; #pragma unroll
;         for (int a = 0; a < 2; ++a)
; #pragma unroll
;             for (int b = 0; b < 2; ++b)
; #pragma unroll
;                 for (int m = 0; m < 4; ++m)
; #pragma unroll
;                     for (int n = 0; n < 2; ++n) acc[a][b][m][n] = (f32x4){0.f, 0.f, 0.f, 0.f};
;         cur = nxt; cA = nA; cB = nB; lda = nlda; ldb = nldb; ++ui;
;         if (wr == 1) PG8_BAR;
	s_andn2_b64 vcc, exec, s[4:5]
	s_cbranch_vccnz .LBB0_994
	s_barrier
	s_branch .LBB0_994
